# baseline (speedup 1.0000x reference)
; #define LAS __attribute__((address_space(3)))
; __device__ __forceinline__ float logsigmoid_fast(float x) { return fminf(x, 0.f) - __logf(1.0f + __expf(-fabsf(x))); }
; template <int KIND, int MODE>
; __device__ __forceinline__ void scan_unit(Frame& F, int layer, int h, int vhalf, int grp) {
;     ...
;         for (int i = 0; i < 2; ++i) { const int e = tid + 512 * i; *(LAS u32x4*)(VS + (e >> 4) * VST + (e & 15) * 8) = pv[i]; }
;         if (KIND == 0) {
; #pragma unroll
;             for (int i = 0; i < 2; ++i) { const int c = tid + 512 * i, t = c >> 4, dc = (c & 15) * 8; const bf16_t* rp = proj + (size_t)(tb + t) * NP + h * 128 + dc;
;                 if (MODE == 1) *(LAS u32x4*)(QS + t * QST + dc) = pq[i];
;                 *(LAS u32x4*)(KS + t * QST + dc) = pk[i]; }
;             X[tid] = pl0; X[tid + 512] = pl1;
;             __syncthreads();
;             float bc[RPT]; float run = 0.f;
; #pragma unroll
;             for (int i = 0; i < RPT; ++i) { const LAS f32x4* lr = (const LAS f32x4*)(X + (tq * RPT + i) * 16); float z = bl;
; #pragma unroll
;                 for (int r = 0; r < 4; ++r) { const f32x4 l4 = lr[r]; z += l4[0] * wl[4 * r] + l4[1] * wl[4 * r + 1] + l4[2] * wl[4 * r + 2] + l4[3] * wl[4 * r + 3]; }
;                 run += logsigmoid_fast(z) * (1.0f / 16.0f); bc[i] = run; }
;             X[1024 + tq * 128 + d] = run;
.LBB0_424:
	v_add_u32_e32 v50, v92, v97
	ds_write_b128 v50, v[2:5]
	v_add_u32_e32 v50, v92, v98
	ds_write_b128 v50, v[6:9]
	v_add_u32_e32 v50, v0, v97
	ds_write_b128 v50, v[10:13] offset:33792
	v_add_u32_e32 v50, v0, v98
	ds_write_b128 v50, v[14:17] offset:33792
	ds_write2st64_b32 v93, v61, v60 offset1:8
	s_waitcnt lgkmcnt(0)
	s_barrier
	ds_read2_b32 v[180:181], v94 offset0:0 offset1:16
	ds_read2_b32 v[182:183], v94 offset0:1 offset1:17
	ds_read2_b32 v[184:185], v94 offset0:2 offset1:18
	ds_read2_b32 v[186:187], v94 offset0:3 offset1:19
	ds_read2_b32 v[188:189], v94 offset0:4 offset1:20
	ds_read2_b32 v[190:191], v94 offset0:5 offset1:21
	ds_read2_b32 v[192:193], v94 offset0:6 offset1:22
	ds_read2_b32 v[194:195], v94 offset0:7 offset1:23
	ds_read2_b32 v[196:197], v94 offset0:8 offset1:24
	ds_read2_b32 v[198:199], v94 offset0:9 offset1:25
	ds_read2_b32 v[200:201], v94 offset0:10 offset1:26
	ds_read2_b32 v[202:203], v94 offset0:11 offset1:27
	ds_read2_b32 v[204:205], v94 offset0:12 offset1:28
	ds_read2_b32 v[206:207], v94 offset0:13 offset1:29
	ds_read2_b32 v[208:209], v94 offset0:14 offset1:30
	ds_read2_b32 v[210:211], v94 offset0:15 offset1:31
	s_waitcnt lgkmcnt(8)
	v_pk_mul_f32 v[212:213], v[76:77], v[182:183] op_sel:[0,0] op_sel_hi:[0,1]
	v_pk_fma_f32 v[212:213], v[74:75], v[180:181], v[212:213] op_sel:[1,0,0] op_sel_hi:[1,1,1]
	v_pk_fma_f32 v[212:213], v[76:77], v[184:185], v[212:213] op_sel:[1,0,0] op_sel_hi:[1,1,1]
	v_pk_fma_f32 v[212:213], v[78:79], v[186:187], v[212:213] op_sel:[0,0,0] op_sel_hi:[0,1,1]
	v_pk_add_f32 v[214:215], v[90:91], v[212:213] op_sel:[1,0] op_sel_hi:[1,1]
	v_pk_mul_f32 v[212:213], v[80:81], v[190:191] op_sel:[0,0] op_sel_hi:[0,1]
	v_pk_fma_f32 v[212:213], v[78:79], v[188:189], v[212:213] op_sel:[1,0,0] op_sel_hi:[1,1,1]
	v_pk_fma_f32 v[212:213], v[80:81], v[192:193], v[212:213] op_sel:[1,0,0] op_sel_hi:[1,1,1]
	v_pk_fma_f32 v[212:213], v[82:83], v[194:195], v[212:213] op_sel:[0,0,0] op_sel_hi:[0,1,1]
	v_pk_add_f32 v[214:215], v[214:215], v[212:213]
	ds_read2_b32 v[180:181], v94 offset0:32 offset1:48
	ds_read2_b32 v[182:183], v94 offset0:33 offset1:49
	ds_read2_b32 v[184:185], v94 offset0:34 offset1:50
	ds_read2_b32 v[186:187], v94 offset0:35 offset1:51
	ds_read2_b32 v[188:189], v94 offset0:36 offset1:52
	ds_read2_b32 v[190:191], v94 offset0:37 offset1:53
	ds_read2_b32 v[192:193], v94 offset0:38 offset1:54
	ds_read2_b32 v[194:195], v94 offset0:39 offset1:55
	s_waitcnt lgkmcnt(8)
	v_pk_mul_f32 v[212:213], v[84:85], v[198:199] op_sel:[0,0] op_sel_hi:[0,1]
	v_pk_fma_f32 v[212:213], v[82:83], v[196:197], v[212:213] op_sel:[1,0,0] op_sel_hi:[1,1,1]
	v_pk_fma_f32 v[212:213], v[84:85], v[200:201], v[212:213] op_sel:[1,0,0] op_sel_hi:[1,1,1]
	v_pk_fma_f32 v[212:213], v[86:87], v[202:203], v[212:213] op_sel:[0,0,0] op_sel_hi:[0,1,1]
	v_pk_add_f32 v[214:215], v[214:215], v[212:213]
	v_pk_mul_f32 v[212:213], v[88:89], v[206:207] op_sel:[0,0] op_sel_hi:[0,1]
	v_pk_fma_f32 v[212:213], v[86:87], v[204:205], v[212:213] op_sel:[1,0,0] op_sel_hi:[1,1,1]
	v_pk_fma_f32 v[212:213], v[88:89], v[208:209], v[212:213] op_sel:[1,0,0] op_sel_hi:[1,1,1]
	v_pk_fma_f32 v[212:213], v[90:91], v[210:211], v[212:213] op_sel:[0,0,0] op_sel_hi:[0,1,1]
	v_pk_add_f32 v[214:215], v[214:215], v[212:213]
	ds_read2_b32 v[196:197], v94 offset0:40 offset1:56
	ds_read2_b32 v[198:199], v94 offset0:41 offset1:57
	ds_read2_b32 v[200:201], v94 offset0:42 offset1:58
	ds_read2_b32 v[202:203], v94 offset0:43 offset1:59
	ds_read2_b32 v[204:205], v94 offset0:44 offset1:60
	ds_read2_b32 v[206:207], v94 offset0:45 offset1:61
	ds_read2_b32 v[208:209], v94 offset0:46 offset1:62
	ds_read2_b32 v[210:211], v94 offset0:47 offset1:63
	v_min_f32_e32 v216, 0, v214
	v_min_f32_e32 v217, 0, v215
	v_mul_f32_e64 v214, |v214|, s65
	v_mul_f32_e64 v215, |v215|, s65
	v_exp_f32_e32 v214, v214
	v_exp_f32_e32 v215, v215
	v_add_f32_e32 v214, 1.0, v214
	v_add_f32_e32 v215, 1.0, v215
	v_log_f32_e32 v214, v214
	v_log_f32_e32 v215, v215
	v_mul_f32_e32 v212, 0x3f317217, v214
	v_mul_f32_e32 v213, 0x3f317217, v215
	v_fma_f32 v212, v214, s75, -v212
	v_fma_f32 v213, v215, s75, -v213
	v_fmac_f32_e32 v212, 0x3377d1cf, v214
	v_fmac_f32_e32 v213, 0x3377d1cf, v215
	v_fmac_f32_e32 v212, 0x3f317217, v214
	v_fmac_f32_e32 v213, 0x3f317217, v215
	v_sub_f32_e32 v214, v216, v212
	v_sub_f32_e32 v215, v217, v213
	v_fma_f32 v50, v214, s64, 0
	v_fmamk_f32 v51, v215, 0x3d800000, v50
	s_waitcnt lgkmcnt(8)
	v_pk_mul_f32 v[212:213], v[76:77], v[182:183] op_sel:[0,0] op_sel_hi:[0,1]
	v_pk_fma_f32 v[212:213], v[74:75], v[180:181], v[212:213] op_sel:[1,0,0] op_sel_hi:[1,1,1]
	v_pk_fma_f32 v[212:213], v[76:77], v[184:185], v[212:213] op_sel:[1,0,0] op_sel_hi:[1,1,1]
	v_pk_fma_f32 v[212:213], v[78:79], v[186:187], v[212:213] op_sel:[0,0,0] op_sel_hi:[0,1,1]
	v_pk_add_f32 v[214:215], v[90:91], v[212:213] op_sel:[1,0] op_sel_hi:[1,1]
	v_pk_mul_f32 v[212:213], v[80:81], v[190:191] op_sel:[0,0] op_sel_hi:[0,1]
	v_pk_fma_f32 v[212:213], v[78:79], v[188:189], v[212:213] op_sel:[1,0,0] op_sel_hi:[1,1,1]
	v_pk_fma_f32 v[212:213], v[80:81], v[192:193], v[212:213] op_sel:[1,0,0] op_sel_hi:[1,1,1]
	v_pk_fma_f32 v[212:213], v[82:83], v[194:195], v[212:213] op_sel:[0,0,0] op_sel_hi:[0,1,1]
	v_pk_add_f32 v[214:215], v[214:215], v[212:213]
	ds_read2_b32 v[180:181], v94 offset0:64 offset1:80
	ds_read2_b32 v[182:183], v94 offset0:65 offset1:81
	ds_read2_b32 v[184:185], v94 offset0:66 offset1:82
	ds_read2_b32 v[186:187], v94 offset0:67 offset1:83
	ds_read2_b32 v[188:189], v94 offset0:68 offset1:84
	ds_read2_b32 v[190:191], v94 offset0:69 offset1:85
	ds_read2_b32 v[192:193], v94 offset0:70 offset1:86
	ds_read2_b32 v[194:195], v94 offset0:71 offset1:87
	s_waitcnt lgkmcnt(8)
; #define LAS __attribute__((address_space(3)))
; __device__ __forceinline__ float logsigmoid_fast(float x) { return fminf(x, 0.f) - __logf(1.0f + __expf(-fabsf(x))); }
; template <int KIND, int MODE>
; __device__ __forceinline__ void scan_unit(Frame& F, int layer, int h, int vhalf, int grp) {
;     ...
;             for (int i = 0; i < RPT; ++i) { const LAS f32x4* lr = (const LAS f32x4*)(X + (tq * RPT + i) * 16); float z = bl;
; #pragma unroll
;                 for (int r = 0; r < 4; ++r) { const f32x4 l4 = lr[r]; z += l4[0] * wl[4 * r] + l4[1] * wl[4 * r + 1] + l4[2] * wl[4 * r + 2] + l4[3] * wl[4 * r + 3]; }
;                 run += logsigmoid_fast(z) * (1.0f / 16.0f); bc[i] = run; }
	v_pk_mul_f32 v[212:213], v[84:85], v[198:199] op_sel:[0,0] op_sel_hi:[0,1]
	v_pk_fma_f32 v[212:213], v[82:83], v[196:197], v[212:213] op_sel:[1,0,0] op_sel_hi:[1,1,1]
	v_pk_fma_f32 v[212:213], v[84:85], v[200:201], v[212:213] op_sel:[1,0,0] op_sel_hi:[1,1,1]
	v_pk_fma_f32 v[212:213], v[86:87], v[202:203], v[212:213] op_sel:[0,0,0] op_sel_hi:[0,1,1]
	v_pk_add_f32 v[214:215], v[214:215], v[212:213]
	v_pk_mul_f32 v[212:213], v[88:89], v[206:207] op_sel:[0,0] op_sel_hi:[0,1]
	v_pk_fma_f32 v[212:213], v[86:87], v[204:205], v[212:213] op_sel:[1,0,0] op_sel_hi:[1,1,1]
	v_pk_fma_f32 v[212:213], v[88:89], v[208:209], v[212:213] op_sel:[1,0,0] op_sel_hi:[1,1,1]
	v_pk_fma_f32 v[212:213], v[90:91], v[210:211], v[212:213] op_sel:[0,0,0] op_sel_hi:[0,1,1]
	v_pk_add_f32 v[214:215], v[214:215], v[212:213]
	ds_read2_b32 v[196:197], v94 offset0:72 offset1:88
	ds_read2_b32 v[198:199], v94 offset0:73 offset1:89
	ds_read2_b32 v[200:201], v94 offset0:74 offset1:90
	ds_read2_b32 v[202:203], v94 offset0:75 offset1:91
	ds_read2_b32 v[204:205], v94 offset0:76 offset1:92
	ds_read2_b32 v[206:207], v94 offset0:77 offset1:93
	ds_read2_b32 v[208:209], v94 offset0:78 offset1:94
	ds_read2_b32 v[210:211], v94 offset0:79 offset1:95
	v_min_f32_e32 v216, 0, v214
	v_min_f32_e32 v217, 0, v215
	v_mul_f32_e64 v214, |v214|, s65
	v_mul_f32_e64 v215, |v215|, s65
	v_exp_f32_e32 v214, v214
	v_exp_f32_e32 v215, v215
	v_add_f32_e32 v214, 1.0, v214
	v_add_f32_e32 v215, 1.0, v215
	v_log_f32_e32 v214, v214
	v_log_f32_e32 v215, v215
	v_mul_f32_e32 v212, 0x3f317217, v214
	v_mul_f32_e32 v213, 0x3f317217, v215
	v_fma_f32 v212, v214, s75, -v212
	v_fma_f32 v213, v215, s75, -v213
	v_fmac_f32_e32 v212, 0x3377d1cf, v214
	v_fmac_f32_e32 v213, 0x3377d1cf, v215
	v_fmac_f32_e32 v212, 0x3f317217, v214
	v_fmac_f32_e32 v213, 0x3f317217, v215
	v_sub_f32_e32 v214, v216, v212
	v_sub_f32_e32 v215, v217, v213
	v_fmamk_f32 v52, v214, 0x3d800000, v51
	v_fmamk_f32 v53, v215, 0x3d800000, v52
	s_waitcnt lgkmcnt(8)
	v_pk_mul_f32 v[212:213], v[76:77], v[182:183] op_sel:[0,0] op_sel_hi:[0,1]
	v_pk_fma_f32 v[212:213], v[74:75], v[180:181], v[212:213] op_sel:[1,0,0] op_sel_hi:[1,1,1]
	v_pk_fma_f32 v[212:213], v[76:77], v[184:185], v[212:213] op_sel:[1,0,0] op_sel_hi:[1,1,1]
	v_pk_fma_f32 v[212:213], v[78:79], v[186:187], v[212:213] op_sel:[0,0,0] op_sel_hi:[0,1,1]
	v_pk_add_f32 v[214:215], v[90:91], v[212:213] op_sel:[1,0] op_sel_hi:[1,1]
	v_pk_mul_f32 v[212:213], v[80:81], v[190:191] op_sel:[0,0] op_sel_hi:[0,1]
	v_pk_fma_f32 v[212:213], v[78:79], v[188:189], v[212:213] op_sel:[1,0,0] op_sel_hi:[1,1,1]
	v_pk_fma_f32 v[212:213], v[80:81], v[192:193], v[212:213] op_sel:[1,0,0] op_sel_hi:[1,1,1]
	v_pk_fma_f32 v[212:213], v[82:83], v[194:195], v[212:213] op_sel:[0,0,0] op_sel_hi:[0,1,1]
	v_pk_add_f32 v[214:215], v[214:215], v[212:213]
	ds_read2_b32 v[180:181], v94 offset0:96 offset1:112
	ds_read2_b32 v[182:183], v94 offset0:97 offset1:113
	ds_read2_b32 v[184:185], v94 offset0:98 offset1:114
	ds_read2_b32 v[186:187], v94 offset0:99 offset1:115
	ds_read2_b32 v[188:189], v94 offset0:100 offset1:116
	ds_read2_b32 v[190:191], v94 offset0:101 offset1:117
	ds_read2_b32 v[192:193], v94 offset0:102 offset1:118
	ds_read2_b32 v[194:195], v94 offset0:103 offset1:119
	s_waitcnt lgkmcnt(8)
	v_pk_mul_f32 v[212:213], v[84:85], v[198:199] op_sel:[0,0] op_sel_hi:[0,1]
	v_pk_fma_f32 v[212:213], v[82:83], v[196:197], v[212:213] op_sel:[1,0,0] op_sel_hi:[1,1,1]
	v_pk_fma_f32 v[212:213], v[84:85], v[200:201], v[212:213] op_sel:[1,0,0] op_sel_hi:[1,1,1]
	v_pk_fma_f32 v[212:213], v[86:87], v[202:203], v[212:213] op_sel:[0,0,0] op_sel_hi:[0,1,1]
	v_pk_add_f32 v[214:215], v[214:215], v[212:213]
	v_pk_mul_f32 v[212:213], v[88:89], v[206:207] op_sel:[0,0] op_sel_hi:[0,1]
	v_pk_fma_f32 v[212:213], v[86:87], v[204:205], v[212:213] op_sel:[1,0,0] op_sel_hi:[1,1,1]
	v_pk_fma_f32 v[212:213], v[88:89], v[208:209], v[212:213] op_sel:[1,0,0] op_sel_hi:[1,1,1]
	v_pk_fma_f32 v[212:213], v[90:91], v[210:211], v[212:213] op_sel:[0,0,0] op_sel_hi:[0,1,1]
	v_pk_add_f32 v[214:215], v[214:215], v[212:213]
	ds_read2_b32 v[196:197], v94 offset0:104 offset1:120
	ds_read2_b32 v[198:199], v94 offset0:105 offset1:121
	ds_read2_b32 v[200:201], v94 offset0:106 offset1:122
	ds_read2_b32 v[202:203], v94 offset0:107 offset1:123
	ds_read2_b32 v[204:205], v94 offset0:108 offset1:124
	ds_read2_b32 v[206:207], v94 offset0:109 offset1:125
	ds_read2_b32 v[208:209], v94 offset0:110 offset1:126
	ds_read2_b32 v[210:211], v94 offset0:111 offset1:127
	v_min_f32_e32 v216, 0, v214
	v_min_f32_e32 v217, 0, v215
	v_mul_f32_e64 v214, |v214|, s65
	v_mul_f32_e64 v215, |v215|, s65
	v_exp_f32_e32 v214, v214
	v_exp_f32_e32 v215, v215
	v_add_f32_e32 v214, 1.0, v214
	v_add_f32_e32 v215, 1.0, v215
	v_log_f32_e32 v214, v214
	v_log_f32_e32 v215, v215
	v_mul_f32_e32 v212, 0x3f317217, v214
	v_mul_f32_e32 v213, 0x3f317217, v215
	v_fma_f32 v212, v214, s75, -v212
	v_fma_f32 v213, v215, s75, -v213
	v_fmac_f32_e32 v212, 0x3377d1cf, v214
	v_fmac_f32_e32 v213, 0x3377d1cf, v215
	v_fmac_f32_e32 v212, 0x3f317217, v214
	v_fmac_f32_e32 v213, 0x3f317217, v215
	v_sub_f32_e32 v214, v216, v212
	v_sub_f32_e32 v215, v217, v213
	v_fmamk_f32 v54, v214, 0x3d800000, v53
	v_fmamk_f32 v55, v215, 0x3d800000, v54
	s_waitcnt lgkmcnt(8)
; #define LAS __attribute__((address_space(3)))
; __device__ __forceinline__ float logsigmoid_fast(float x) { return fminf(x, 0.f) - __logf(1.0f + __expf(-fabsf(x))); }
; template <int KIND, int MODE>
; __device__ __forceinline__ void scan_unit(Frame& F, int layer, int h, int vhalf, int grp) {
;     ...
;             for (int i = 0; i < RPT; ++i) { const LAS f32x4* lr = (const LAS f32x4*)(X + (tq * RPT + i) * 16); float z = bl;
; #pragma unroll
;                 for (int r = 0; r < 4; ++r) { const f32x4 l4 = lr[r]; z += l4[0] * wl[4 * r] + l4[1] * wl[4 * r + 1] + l4[2] * wl[4 * r + 2] + l4[3] * wl[4 * r + 3]; }
;                 run += logsigmoid_fast(z) * (1.0f / 16.0f); bc[i] = run; }
	v_pk_mul_f32 v[212:213], v[76:77], v[182:183] op_sel:[0,0] op_sel_hi:[0,1]
	v_pk_fma_f32 v[212:213], v[74:75], v[180:181], v[212:213] op_sel:[1,0,0] op_sel_hi:[1,1,1]
	v_pk_fma_f32 v[212:213], v[76:77], v[184:185], v[212:213] op_sel:[1,0,0] op_sel_hi:[1,1,1]
	v_pk_fma_f32 v[212:213], v[78:79], v[186:187], v[212:213] op_sel:[0,0,0] op_sel_hi:[0,1,1]
	v_pk_add_f32 v[214:215], v[90:91], v[212:213] op_sel:[1,0] op_sel_hi:[1,1]
	v_pk_mul_f32 v[212:213], v[80:81], v[190:191] op_sel:[0,0] op_sel_hi:[0,1]
	v_pk_fma_f32 v[212:213], v[78:79], v[188:189], v[212:213] op_sel:[1,0,0] op_sel_hi:[1,1,1]
	v_pk_fma_f32 v[212:213], v[80:81], v[192:193], v[212:213] op_sel:[1,0,0] op_sel_hi:[1,1,1]
	v_pk_fma_f32 v[212:213], v[82:83], v[194:195], v[212:213] op_sel:[0,0,0] op_sel_hi:[0,1,1]
	v_pk_add_f32 v[214:215], v[214:215], v[212:213]
	ds_read2_b32 v[180:181], v94 offset0:128 offset1:144
	ds_read2_b32 v[182:183], v94 offset0:129 offset1:145
	ds_read2_b32 v[184:185], v94 offset0:130 offset1:146
	ds_read2_b32 v[186:187], v94 offset0:131 offset1:147
	ds_read2_b32 v[188:189], v94 offset0:132 offset1:148
	ds_read2_b32 v[190:191], v94 offset0:133 offset1:149
	ds_read2_b32 v[192:193], v94 offset0:134 offset1:150
	ds_read2_b32 v[194:195], v94 offset0:135 offset1:151
	s_waitcnt lgkmcnt(8)
	v_pk_mul_f32 v[212:213], v[84:85], v[198:199] op_sel:[0,0] op_sel_hi:[0,1]
	v_pk_fma_f32 v[212:213], v[82:83], v[196:197], v[212:213] op_sel:[1,0,0] op_sel_hi:[1,1,1]
	v_pk_fma_f32 v[212:213], v[84:85], v[200:201], v[212:213] op_sel:[1,0,0] op_sel_hi:[1,1,1]
	v_pk_fma_f32 v[212:213], v[86:87], v[202:203], v[212:213] op_sel:[0,0,0] op_sel_hi:[0,1,1]
	v_pk_add_f32 v[214:215], v[214:215], v[212:213]
	v_pk_mul_f32 v[212:213], v[88:89], v[206:207] op_sel:[0,0] op_sel_hi:[0,1]
	v_pk_fma_f32 v[212:213], v[86:87], v[204:205], v[212:213] op_sel:[1,0,0] op_sel_hi:[1,1,1]
	v_pk_fma_f32 v[212:213], v[88:89], v[208:209], v[212:213] op_sel:[1,0,0] op_sel_hi:[1,1,1]
	v_pk_fma_f32 v[212:213], v[90:91], v[210:211], v[212:213] op_sel:[0,0,0] op_sel_hi:[0,1,1]
	v_pk_add_f32 v[214:215], v[214:215], v[212:213]
	ds_read2_b32 v[196:197], v94 offset0:136 offset1:152
	ds_read2_b32 v[198:199], v94 offset0:137 offset1:153
	ds_read2_b32 v[200:201], v94 offset0:138 offset1:154
	ds_read2_b32 v[202:203], v94 offset0:139 offset1:155
	ds_read2_b32 v[204:205], v94 offset0:140 offset1:156
	ds_read2_b32 v[206:207], v94 offset0:141 offset1:157
	ds_read2_b32 v[208:209], v94 offset0:142 offset1:158
	ds_read2_b32 v[210:211], v94 offset0:143 offset1:159
	v_min_f32_e32 v216, 0, v214
	v_min_f32_e32 v217, 0, v215
	v_mul_f32_e64 v214, |v214|, s65
	v_mul_f32_e64 v215, |v215|, s65
	v_exp_f32_e32 v214, v214
	v_exp_f32_e32 v215, v215
	v_add_f32_e32 v214, 1.0, v214
	v_add_f32_e32 v215, 1.0, v215
	v_log_f32_e32 v214, v214
	v_log_f32_e32 v215, v215
	v_mul_f32_e32 v212, 0x3f317217, v214
	v_mul_f32_e32 v213, 0x3f317217, v215
	v_fma_f32 v212, v214, s75, -v212
	v_fma_f32 v213, v215, s75, -v213
	v_fmac_f32_e32 v212, 0x3377d1cf, v214
	v_fmac_f32_e32 v213, 0x3377d1cf, v215
	v_fmac_f32_e32 v212, 0x3f317217, v214
	v_fmac_f32_e32 v213, 0x3f317217, v215
	v_sub_f32_e32 v214, v216, v212
	v_sub_f32_e32 v215, v217, v213
	v_fmamk_f32 v56, v214, 0x3d800000, v55
	v_fmamk_f32 v124, v215, 0x3d800000, v56
	s_waitcnt lgkmcnt(8)
	v_pk_mul_f32 v[212:213], v[76:77], v[182:183] op_sel:[0,0] op_sel_hi:[0,1]
	v_pk_fma_f32 v[212:213], v[74:75], v[180:181], v[212:213] op_sel:[1,0,0] op_sel_hi:[1,1,1]
	v_pk_fma_f32 v[212:213], v[76:77], v[184:185], v[212:213] op_sel:[1,0,0] op_sel_hi:[1,1,1]
	v_pk_fma_f32 v[212:213], v[78:79], v[186:187], v[212:213] op_sel:[0,0,0] op_sel_hi:[0,1,1]
	v_pk_add_f32 v[214:215], v[90:91], v[212:213] op_sel:[1,0] op_sel_hi:[1,1]
	v_pk_mul_f32 v[212:213], v[80:81], v[190:191] op_sel:[0,0] op_sel_hi:[0,1]
	v_pk_fma_f32 v[212:213], v[78:79], v[188:189], v[212:213] op_sel:[1,0,0] op_sel_hi:[1,1,1]
	v_pk_fma_f32 v[212:213], v[80:81], v[192:193], v[212:213] op_sel:[1,0,0] op_sel_hi:[1,1,1]
	v_pk_fma_f32 v[212:213], v[82:83], v[194:195], v[212:213] op_sel:[0,0,0] op_sel_hi:[0,1,1]
	v_pk_add_f32 v[214:215], v[214:215], v[212:213]
	ds_read2_b32 v[180:181], v94 offset0:160 offset1:176
	ds_read2_b32 v[182:183], v94 offset0:161 offset1:177
	ds_read2_b32 v[184:185], v94 offset0:162 offset1:178
	ds_read2_b32 v[186:187], v94 offset0:163 offset1:179
	ds_read2_b32 v[188:189], v94 offset0:164 offset1:180
	ds_read2_b32 v[190:191], v94 offset0:165 offset1:181
	ds_read2_b32 v[192:193], v94 offset0:166 offset1:182
	ds_read2_b32 v[194:195], v94 offset0:167 offset1:183
	s_waitcnt lgkmcnt(8)
	v_pk_mul_f32 v[212:213], v[84:85], v[198:199] op_sel:[0,0] op_sel_hi:[0,1]
	v_pk_fma_f32 v[212:213], v[82:83], v[196:197], v[212:213] op_sel:[1,0,0] op_sel_hi:[1,1,1]
	v_pk_fma_f32 v[212:213], v[84:85], v[200:201], v[212:213] op_sel:[1,0,0] op_sel_hi:[1,1,1]
	v_pk_fma_f32 v[212:213], v[86:87], v[202:203], v[212:213] op_sel:[0,0,0] op_sel_hi:[0,1,1]
	v_pk_add_f32 v[214:215], v[214:215], v[212:213]
	v_pk_mul_f32 v[212:213], v[88:89], v[206:207] op_sel:[0,0] op_sel_hi:[0,1]
	v_pk_fma_f32 v[212:213], v[86:87], v[204:205], v[212:213] op_sel:[1,0,0] op_sel_hi:[1,1,1]
	v_pk_fma_f32 v[212:213], v[88:89], v[208:209], v[212:213] op_sel:[1,0,0] op_sel_hi:[1,1,1]
	v_pk_fma_f32 v[212:213], v[90:91], v[210:211], v[212:213] op_sel:[0,0,0] op_sel_hi:[0,1,1]
	v_pk_add_f32 v[214:215], v[214:215], v[212:213]
	ds_read2_b32 v[196:197], v94 offset0:168 offset1:184
	ds_read2_b32 v[198:199], v94 offset0:169 offset1:185
	ds_read2_b32 v[200:201], v94 offset0:170 offset1:186
	ds_read2_b32 v[202:203], v94 offset0:171 offset1:187
	ds_read2_b32 v[204:205], v94 offset0:172 offset1:188
	ds_read2_b32 v[206:207], v94 offset0:173 offset1:189
	ds_read2_b32 v[208:209], v94 offset0:174 offset1:190
	ds_read2_b32 v[210:211], v94 offset0:175 offset1:191
	v_min_f32_e32 v216, 0, v214
	v_min_f32_e32 v217, 0, v215
	v_mul_f32_e64 v214, |v214|, s65
	v_mul_f32_e64 v215, |v215|, s65
	v_exp_f32_e32 v214, v214
	v_exp_f32_e32 v215, v215
	v_add_f32_e32 v214, 1.0, v214
	v_add_f32_e32 v215, 1.0, v215
	v_log_f32_e32 v214, v214
	v_log_f32_e32 v215, v215
	v_mul_f32_e32 v212, 0x3f317217, v214
	v_mul_f32_e32 v213, 0x3f317217, v215
	v_fma_f32 v212, v214, s75, -v212
	v_fma_f32 v213, v215, s75, -v213
	v_fmac_f32_e32 v212, 0x3377d1cf, v214
	v_fmac_f32_e32 v213, 0x3377d1cf, v215
	v_fmac_f32_e32 v212, 0x3f317217, v214
	v_fmac_f32_e32 v213, 0x3f317217, v215
	v_sub_f32_e32 v214, v216, v212
	v_sub_f32_e32 v215, v217, v213
	v_fmamk_f32 v57, v214, 0x3d800000, v124
	v_fmamk_f32 v125, v215, 0x3d800000, v57
	s_waitcnt lgkmcnt(8)
; #define LAS __attribute__((address_space(3)))
; __device__ __forceinline__ float logsigmoid_fast(float x) { return fminf(x, 0.f) - __logf(1.0f + __expf(-fabsf(x))); }
; template <int KIND, int MODE>
; __device__ __forceinline__ void scan_unit(Frame& F, int layer, int h, int vhalf, int grp) {
;     ...
;             for (int i = 0; i < RPT; ++i) { const LAS f32x4* lr = (const LAS f32x4*)(X + (tq * RPT + i) * 16); float z = bl;
; #pragma unroll
;                 for (int r = 0; r < 4; ++r) { const f32x4 l4 = lr[r]; z += l4[0] * wl[4 * r] + l4[1] * wl[4 * r + 1] + l4[2] * wl[4 * r + 2] + l4[3] * wl[4 * r + 3]; }
;                 run += logsigmoid_fast(z) * (1.0f / 16.0f); bc[i] = run; }
	v_pk_mul_f32 v[212:213], v[76:77], v[182:183] op_sel:[0,0] op_sel_hi:[0,1]
	v_pk_fma_f32 v[212:213], v[74:75], v[180:181], v[212:213] op_sel:[1,0,0] op_sel_hi:[1,1,1]
	v_pk_fma_f32 v[212:213], v[76:77], v[184:185], v[212:213] op_sel:[1,0,0] op_sel_hi:[1,1,1]
	v_pk_fma_f32 v[212:213], v[78:79], v[186:187], v[212:213] op_sel:[0,0,0] op_sel_hi:[0,1,1]
	v_pk_add_f32 v[214:215], v[90:91], v[212:213] op_sel:[1,0] op_sel_hi:[1,1]
	v_pk_mul_f32 v[212:213], v[80:81], v[190:191] op_sel:[0,0] op_sel_hi:[0,1]
	v_pk_fma_f32 v[212:213], v[78:79], v[188:189], v[212:213] op_sel:[1,0,0] op_sel_hi:[1,1,1]
	v_pk_fma_f32 v[212:213], v[80:81], v[192:193], v[212:213] op_sel:[1,0,0] op_sel_hi:[1,1,1]
	v_pk_fma_f32 v[212:213], v[82:83], v[194:195], v[212:213] op_sel:[0,0,0] op_sel_hi:[0,1,1]
	v_pk_add_f32 v[214:215], v[214:215], v[212:213]
	ds_read2_b32 v[180:181], v94 offset0:192 offset1:208
	ds_read2_b32 v[182:183], v94 offset0:193 offset1:209
	ds_read2_b32 v[184:185], v94 offset0:194 offset1:210
	ds_read2_b32 v[186:187], v94 offset0:195 offset1:211
	ds_read2_b32 v[188:189], v94 offset0:196 offset1:212
	ds_read2_b32 v[190:191], v94 offset0:197 offset1:213
	ds_read2_b32 v[192:193], v94 offset0:198 offset1:214
	ds_read2_b32 v[194:195], v94 offset0:199 offset1:215
	s_waitcnt lgkmcnt(8)
	v_pk_mul_f32 v[212:213], v[84:85], v[198:199] op_sel:[0,0] op_sel_hi:[0,1]
	v_pk_fma_f32 v[212:213], v[82:83], v[196:197], v[212:213] op_sel:[1,0,0] op_sel_hi:[1,1,1]
	v_pk_fma_f32 v[212:213], v[84:85], v[200:201], v[212:213] op_sel:[1,0,0] op_sel_hi:[1,1,1]
	v_pk_fma_f32 v[212:213], v[86:87], v[202:203], v[212:213] op_sel:[0,0,0] op_sel_hi:[0,1,1]
	v_pk_add_f32 v[214:215], v[214:215], v[212:213]
	v_pk_mul_f32 v[212:213], v[88:89], v[206:207] op_sel:[0,0] op_sel_hi:[0,1]
	v_pk_fma_f32 v[212:213], v[86:87], v[204:205], v[212:213] op_sel:[1,0,0] op_sel_hi:[1,1,1]
	v_pk_fma_f32 v[212:213], v[88:89], v[208:209], v[212:213] op_sel:[1,0,0] op_sel_hi:[1,1,1]
	v_pk_fma_f32 v[212:213], v[90:91], v[210:211], v[212:213] op_sel:[0,0,0] op_sel_hi:[0,1,1]
	v_pk_add_f32 v[214:215], v[214:215], v[212:213]
	ds_read2_b32 v[196:197], v94 offset0:200 offset1:216
	ds_read2_b32 v[198:199], v94 offset0:201 offset1:217
	ds_read2_b32 v[200:201], v94 offset0:202 offset1:218
	ds_read2_b32 v[202:203], v94 offset0:203 offset1:219
	ds_read2_b32 v[204:205], v94 offset0:204 offset1:220
	ds_read2_b32 v[206:207], v94 offset0:205 offset1:221
	ds_read2_b32 v[208:209], v94 offset0:206 offset1:222
	ds_read2_b32 v[210:211], v94 offset0:207 offset1:223
	v_min_f32_e32 v216, 0, v214
	v_min_f32_e32 v217, 0, v215
	v_mul_f32_e64 v214, |v214|, s65
	v_mul_f32_e64 v215, |v215|, s65
	v_exp_f32_e32 v214, v214
	v_exp_f32_e32 v215, v215
	v_add_f32_e32 v214, 1.0, v214
	v_add_f32_e32 v215, 1.0, v215
	v_log_f32_e32 v214, v214
	v_log_f32_e32 v215, v215
	v_mul_f32_e32 v212, 0x3f317217, v214
	v_mul_f32_e32 v213, 0x3f317217, v215
	v_fma_f32 v212, v214, s75, -v212
	v_fma_f32 v213, v215, s75, -v213
	v_fmac_f32_e32 v212, 0x3377d1cf, v214
	v_fmac_f32_e32 v213, 0x3377d1cf, v215
	v_fmac_f32_e32 v212, 0x3f317217, v214
	v_fmac_f32_e32 v213, 0x3f317217, v215
	v_sub_f32_e32 v214, v216, v212
	v_sub_f32_e32 v215, v217, v213
	v_fmamk_f32 v126, v214, 0x3d800000, v125
	v_fmamk_f32 v127, v215, 0x3d800000, v126
	s_waitcnt lgkmcnt(8)
	v_pk_mul_f32 v[212:213], v[76:77], v[182:183] op_sel:[0,0] op_sel_hi:[0,1]
	v_pk_fma_f32 v[212:213], v[74:75], v[180:181], v[212:213] op_sel:[1,0,0] op_sel_hi:[1,1,1]
	v_pk_fma_f32 v[212:213], v[76:77], v[184:185], v[212:213] op_sel:[1,0,0] op_sel_hi:[1,1,1]
	v_pk_fma_f32 v[212:213], v[78:79], v[186:187], v[212:213] op_sel:[0,0,0] op_sel_hi:[0,1,1]
	v_pk_add_f32 v[214:215], v[90:91], v[212:213] op_sel:[1,0] op_sel_hi:[1,1]
	v_pk_mul_f32 v[212:213], v[80:81], v[190:191] op_sel:[0,0] op_sel_hi:[0,1]
	v_pk_fma_f32 v[212:213], v[78:79], v[188:189], v[212:213] op_sel:[1,0,0] op_sel_hi:[1,1,1]
	v_pk_fma_f32 v[212:213], v[80:81], v[192:193], v[212:213] op_sel:[1,0,0] op_sel_hi:[1,1,1]
	v_pk_fma_f32 v[212:213], v[82:83], v[194:195], v[212:213] op_sel:[0,0,0] op_sel_hi:[0,1,1]
	v_pk_add_f32 v[214:215], v[214:215], v[212:213]
	ds_read2_b32 v[180:181], v94 offset0:224 offset1:240
	ds_read2_b32 v[182:183], v94 offset0:225 offset1:241
	ds_read2_b32 v[184:185], v94 offset0:226 offset1:242
	ds_read2_b32 v[186:187], v94 offset0:227 offset1:243
	ds_read2_b32 v[188:189], v94 offset0:228 offset1:244
	ds_read2_b32 v[190:191], v94 offset0:229 offset1:245
	ds_read2_b32 v[192:193], v94 offset0:230 offset1:246
	ds_read2_b32 v[194:195], v94 offset0:231 offset1:247
	s_waitcnt lgkmcnt(8)
	v_pk_mul_f32 v[212:213], v[84:85], v[198:199] op_sel:[0,0] op_sel_hi:[0,1]
	v_pk_fma_f32 v[212:213], v[82:83], v[196:197], v[212:213] op_sel:[1,0,0] op_sel_hi:[1,1,1]
	v_pk_fma_f32 v[212:213], v[84:85], v[200:201], v[212:213] op_sel:[1,0,0] op_sel_hi:[1,1,1]
	v_pk_fma_f32 v[212:213], v[86:87], v[202:203], v[212:213] op_sel:[0,0,0] op_sel_hi:[0,1,1]
	v_pk_add_f32 v[214:215], v[214:215], v[212:213]
	v_pk_mul_f32 v[212:213], v[88:89], v[206:207] op_sel:[0,0] op_sel_hi:[0,1]
	v_pk_fma_f32 v[212:213], v[86:87], v[204:205], v[212:213] op_sel:[1,0,0] op_sel_hi:[1,1,1]
	v_pk_fma_f32 v[212:213], v[88:89], v[208:209], v[212:213] op_sel:[1,0,0] op_sel_hi:[1,1,1]
	v_pk_fma_f32 v[212:213], v[90:91], v[210:211], v[212:213] op_sel:[0,0,0] op_sel_hi:[0,1,1]
	v_pk_add_f32 v[214:215], v[214:215], v[212:213]
	ds_read2_b32 v[196:197], v94 offset0:232 offset1:248
	ds_read2_b32 v[198:199], v94 offset0:233 offset1:249
	ds_read2_b32 v[200:201], v94 offset0:234 offset1:250
	ds_read2_b32 v[202:203], v94 offset0:235 offset1:251
	ds_read2_b32 v[204:205], v94 offset0:236 offset1:252
	ds_read2_b32 v[206:207], v94 offset0:237 offset1:253
	ds_read2_b32 v[208:209], v94 offset0:238 offset1:254
	ds_read2_b32 v[210:211], v94 offset0:239 offset1:255
	v_min_f32_e32 v216, 0, v214
	v_min_f32_e32 v217, 0, v215
	v_mul_f32_e64 v214, |v214|, s65
	v_mul_f32_e64 v215, |v215|, s65
	v_exp_f32_e32 v214, v214
	v_exp_f32_e32 v215, v215
	v_add_f32_e32 v214, 1.0, v214
	v_add_f32_e32 v215, 1.0, v215
	v_log_f32_e32 v214, v214
	v_log_f32_e32 v215, v215
	v_mul_f32_e32 v212, 0x3f317217, v214
	v_mul_f32_e32 v213, 0x3f317217, v215
	v_fma_f32 v212, v214, s75, -v212
	v_fma_f32 v213, v215, s75, -v213
	v_fmac_f32_e32 v212, 0x3377d1cf, v214
	v_fmac_f32_e32 v213, 0x3377d1cf, v215
	v_fmac_f32_e32 v212, 0x3f317217, v214
	v_fmac_f32_e32 v213, 0x3f317217, v215
	v_sub_f32_e32 v214, v216, v212
	v_sub_f32_e32 v215, v217, v213
	v_fmamk_f32 v128, v214, 0x3d800000, v127
	v_fmamk_f32 v129, v215, 0x3d800000, v128
	s_waitcnt lgkmcnt(8)
; #define LAS __attribute__((address_space(3)))
; __device__ __forceinline__ float logsigmoid_fast(float x) { return fminf(x, 0.f) - __logf(1.0f + __expf(-fabsf(x))); }
; template <int KIND, int MODE>
; __device__ __forceinline__ void scan_unit(Frame& F, int layer, int h, int vhalf, int grp) {
;     ...
;             for (int i = 0; i < RPT; ++i) { const LAS f32x4* lr = (const LAS f32x4*)(X + (tq * RPT + i) * 16); float z = bl;
; #pragma unroll
;                 for (int r = 0; r < 4; ++r) { const f32x4 l4 = lr[r]; z += l4[0] * wl[4 * r] + l4[1] * wl[4 * r + 1] + l4[2] * wl[4 * r + 2] + l4[3] * wl[4 * r + 3]; }
;                 run += logsigmoid_fast(z) * (1.0f / 16.0f); bc[i] = run; }
;             X[1024 + tq * 128 + d] = run;
;             __syncthreads();
	v_pk_mul_f32 v[212:213], v[76:77], v[182:183] op_sel:[0,0] op_sel_hi:[0,1]
	v_pk_fma_f32 v[212:213], v[74:75], v[180:181], v[212:213] op_sel:[1,0,0] op_sel_hi:[1,1,1]
	v_pk_fma_f32 v[212:213], v[76:77], v[184:185], v[212:213] op_sel:[1,0,0] op_sel_hi:[1,1,1]
	v_pk_fma_f32 v[212:213], v[78:79], v[186:187], v[212:213] op_sel:[0,0,0] op_sel_hi:[0,1,1]
	v_pk_add_f32 v[214:215], v[90:91], v[212:213] op_sel:[1,0] op_sel_hi:[1,1]
	v_pk_mul_f32 v[212:213], v[80:81], v[190:191] op_sel:[0,0] op_sel_hi:[0,1]
	v_pk_fma_f32 v[212:213], v[78:79], v[188:189], v[212:213] op_sel:[1,0,0] op_sel_hi:[1,1,1]
	v_pk_fma_f32 v[212:213], v[80:81], v[192:193], v[212:213] op_sel:[1,0,0] op_sel_hi:[1,1,1]
	v_pk_fma_f32 v[212:213], v[82:83], v[194:195], v[212:213] op_sel:[0,0,0] op_sel_hi:[0,1,1]
	v_pk_add_f32 v[214:215], v[214:215], v[212:213]
	s_waitcnt lgkmcnt(0)
	v_pk_mul_f32 v[212:213], v[84:85], v[198:199] op_sel:[0,0] op_sel_hi:[0,1]
	v_pk_fma_f32 v[212:213], v[82:83], v[196:197], v[212:213] op_sel:[1,0,0] op_sel_hi:[1,1,1]
	v_pk_fma_f32 v[212:213], v[84:85], v[200:201], v[212:213] op_sel:[1,0,0] op_sel_hi:[1,1,1]
	v_pk_fma_f32 v[212:213], v[86:87], v[202:203], v[212:213] op_sel:[0,0,0] op_sel_hi:[0,1,1]
	v_pk_add_f32 v[214:215], v[214:215], v[212:213]
	v_pk_mul_f32 v[212:213], v[88:89], v[206:207] op_sel:[0,0] op_sel_hi:[0,1]
	v_pk_fma_f32 v[212:213], v[86:87], v[204:205], v[212:213] op_sel:[1,0,0] op_sel_hi:[1,1,1]
	v_pk_fma_f32 v[212:213], v[88:89], v[208:209], v[212:213] op_sel:[1,0,0] op_sel_hi:[1,1,1]
	v_pk_fma_f32 v[212:213], v[90:91], v[210:211], v[212:213] op_sel:[0,0,0] op_sel_hi:[0,1,1]
	v_pk_add_f32 v[214:215], v[214:215], v[212:213]
	v_min_f32_e32 v216, 0, v214
	v_min_f32_e32 v217, 0, v215
	v_mul_f32_e64 v214, |v214|, s65
	v_mul_f32_e64 v215, |v215|, s65
	v_exp_f32_e32 v214, v214
	v_exp_f32_e32 v215, v215
	v_add_f32_e32 v214, 1.0, v214
	v_add_f32_e32 v215, 1.0, v215
	v_log_f32_e32 v214, v214
	v_log_f32_e32 v215, v215
	v_mul_f32_e32 v212, 0x3f317217, v214
	v_mul_f32_e32 v213, 0x3f317217, v215
	v_fma_f32 v212, v214, s75, -v212
	v_fma_f32 v213, v215, s75, -v213
	v_fmac_f32_e32 v212, 0x3377d1cf, v214
	v_fmac_f32_e32 v213, 0x3377d1cf, v215
	v_fmac_f32_e32 v212, 0x3f317217, v214
	v_fmac_f32_e32 v213, 0x3f317217, v215
	v_sub_f32_e32 v214, v216, v212
	v_sub_f32_e32 v215, v217, v213
	v_fmamk_f32 v131, v214, 0x3d800000, v129
	v_fmamk_f32 v132, v215, 0x3d800000, v131
	ds_write_b32 v96, v132 offset:4096
	s_waitcnt lgkmcnt(0)
	s_barrier
; __device__ __forceinline__ unsigned pk2hw(float lo, float hi) { unsigned r; asm("s_nop 1\n\tv_cvt_pk_bf16_f32 %0, %1, %2" : "=v"(r) : "v"(lo), "v"(hi)); return r; }
; template <int KIND, int MODE>
; __device__ __forceinline__ void scan_unit(Frame& F, int layer, int h, int vhalf, int grp) {
;     ...
;             float pre = 0.f, tot = 0.f;
; #pragma unroll
;             for (int qq = 0; qq < NTQ; ++qq) { const float v = X[1024 + qq * 128 + d]; tot += v; if (qq < tq) pre += v; }
;             const float etot = __expf(tot);
;             if (tq == 0) { X[1536 + d] = etot; gtot += tot; }
; #pragma unroll
;             for (int i = 0; i < RPT; ++i) { const int t = tq * RPT + i; const float bcv = bc[i] + pre;
;                 const float kv = bf2f(KS[t * QST + d]); const float eb = __expf(bcv), ib = __builtin_amdgcn_rcpf(eb);
;                 if (MODE == 1) { const float qv = bf2f(QS[t * QST + d]); const unsigned w0 = pk2hw(qv * 0.08838834764831845f * eb, kv * ib); QS[t * QST + d] = (unsigned short)w0; KS[t * QST + d] = (unsigned short)(w0 >> 16); }
;                 K2[t * QST + d] = (unsigned short)pk2hw(kv * (etot * ib), 0.f); }
;             if (PREF && ch + 1 < (grp + 1) * GC) SCAN_LOAD(tb + 64);
	ds_read_b32 v130, v99
	ds_read_b32 v134, v101
	ds_read_b32 v135, v102
	ds_read_b32 v136, v103
	s_waitcnt lgkmcnt(3)
	v_add_f32_e32 v133, 0, v130
	s_waitcnt lgkmcnt(2)
	v_add_f32_e32 v130, v133, v134
	s_waitcnt lgkmcnt(1)
	v_add_f32_e32 v130, v130, v135
	s_waitcnt lgkmcnt(0)
	v_add_f32_e32 v137, v130, v136
	v_mul_f32_e32 v130, 0x3fb8aa3b, v137
	v_exp_f32_e32 v130, v130
	s_and_saveexec_b64 s[0:1], vcc
	v_add_f32_e32 v100, v100, v137
	ds_write_b32 v95, v130 offset:6144
	s_or_b64 exec, exec, s[0:1]
	v_cndmask_b32_e64 v133, 0, v133, s[8:9]
	v_add_f32_e32 v134, v134, v133
	v_cndmask_b32_e64 v133, v133, v134, s[10:11]
	v_add_f32_e32 v134, v135, v133
	v_cndmask_b32_e64 v133, v133, v134, s[12:13]
	v_add_f32_e32 v134, v136, v133
	v_cndmask_b32_e64 v133, v133, v134, s[14:15]
	v_add_f32_e32 v50, v50, v133
	v_mul_f32_e32 v50, 0x3fb8aa3b, v50
	v_exp_f32_e32 v50, v50
	ds_read_u16 v134, v104 offset:33792
	s_cmp_ge_i32 s24, s23
	v_rcp_f32_e32 v50, v50
	s_waitcnt lgkmcnt(0)
	v_lshlrev_b32_e32 v134, 16, v134
	v_mul_f32_e32 v50, v130, v50
	v_mul_f32_e32 v50, v50, v134
	s_nop 1
	v_cvt_pk_bf16_f32 v50, v50, v1
	ds_write_b16 v105, v50
	v_add_f32_e32 v50, v51, v133
	v_mul_f32_e32 v50, 0x3fb8aa3b, v50
	v_exp_f32_e32 v50, v50
	ds_read_u16 v51, v104 offset:34064
	v_rcp_f32_e32 v50, v50
	s_waitcnt lgkmcnt(0)
	v_lshlrev_b32_e32 v51, 16, v51
	v_mul_f32_e32 v50, v130, v50
	v_mul_f32_e32 v50, v50, v51
	s_nop 1
	v_cvt_pk_bf16_f32 v50, v50, v1
	ds_write_b16 v106, v50
	v_add_f32_e32 v50, v52, v133
	v_mul_f32_e32 v50, 0x3fb8aa3b, v50
	v_exp_f32_e32 v50, v50
	ds_read_u16 v51, v104 offset:34336
	v_rcp_f32_e32 v50, v50
	s_waitcnt lgkmcnt(0)
	v_lshlrev_b32_e32 v51, 16, v51
	v_mul_f32_e32 v50, v130, v50
	v_mul_f32_e32 v50, v50, v51
	s_nop 1
	v_cvt_pk_bf16_f32 v50, v50, v1
	ds_write_b16 v107, v50
	v_add_f32_e32 v50, v53, v133
	v_mul_f32_e32 v50, 0x3fb8aa3b, v50
	v_exp_f32_e32 v50, v50
	ds_read_u16 v51, v104 offset:34608
	v_rcp_f32_e32 v50, v50
	s_waitcnt lgkmcnt(0)
	v_lshlrev_b32_e32 v51, 16, v51
	v_mul_f32_e32 v50, v130, v50
	v_mul_f32_e32 v50, v50, v51
	s_nop 1
	v_cvt_pk_bf16_f32 v50, v50, v1
	ds_write_b16 v108, v50
	v_add_f32_e32 v50, v54, v133
	v_mul_f32_e32 v50, 0x3fb8aa3b, v50
	v_exp_f32_e32 v50, v50
	ds_read_u16 v51, v104 offset:34880
	v_rcp_f32_e32 v50, v50
	s_waitcnt lgkmcnt(0)
	v_lshlrev_b32_e32 v51, 16, v51
	v_mul_f32_e32 v50, v130, v50
	v_mul_f32_e32 v50, v50, v51
	s_nop 1
	v_cvt_pk_bf16_f32 v50, v50, v1
	ds_write_b16 v109, v50
	v_add_f32_e32 v50, v55, v133
	v_mul_f32_e32 v50, 0x3fb8aa3b, v50
	v_exp_f32_e32 v50, v50
	ds_read_u16 v51, v104 offset:35152
	v_rcp_f32_e32 v50, v50
	s_waitcnt lgkmcnt(0)
	v_lshlrev_b32_e32 v51, 16, v51
	v_mul_f32_e32 v50, v130, v50
	v_mul_f32_e32 v50, v50, v51
	s_nop 1
	v_cvt_pk_bf16_f32 v50, v50, v1
	ds_write_b16 v110, v50
	v_add_f32_e32 v50, v56, v133
	v_mul_f32_e32 v50, 0x3fb8aa3b, v50
	v_exp_f32_e32 v50, v50
	ds_read_u16 v51, v104 offset:35424
	v_rcp_f32_e32 v50, v50
	s_waitcnt lgkmcnt(0)
	v_lshlrev_b32_e32 v51, 16, v51
	v_mul_f32_e32 v50, v130, v50
	v_mul_f32_e32 v50, v50, v51
	s_nop 1
	v_cvt_pk_bf16_f32 v50, v50, v1
	ds_write_b16 v111, v50
	v_add_f32_e32 v50, v124, v133
	v_mul_f32_e32 v50, 0x3fb8aa3b, v50
	v_exp_f32_e32 v50, v50
	ds_read_u16 v51, v104 offset:35696
	v_rcp_f32_e32 v50, v50
	s_waitcnt lgkmcnt(0)
	v_lshlrev_b32_e32 v51, 16, v51
	v_mul_f32_e32 v50, v130, v50
	v_mul_f32_e32 v50, v50, v51
	s_nop 1
	v_cvt_pk_bf16_f32 v50, v50, v1
	ds_write_b16 v112, v50
	v_add_f32_e32 v50, v57, v133
	v_mul_f32_e32 v50, 0x3fb8aa3b, v50
	v_exp_f32_e32 v50, v50
	ds_read_u16 v51, v104 offset:35968
	v_rcp_f32_e32 v50, v50
	s_waitcnt lgkmcnt(0)
	v_lshlrev_b32_e32 v51, 16, v51
	v_mul_f32_e32 v50, v130, v50
	v_mul_f32_e32 v50, v50, v51
	s_nop 1
	v_cvt_pk_bf16_f32 v50, v50, v1
	ds_write_b16 v113, v50
	v_add_f32_e32 v50, v125, v133
	v_mul_f32_e32 v50, 0x3fb8aa3b, v50
	v_exp_f32_e32 v50, v50
	ds_read_u16 v51, v104 offset:36240
	v_rcp_f32_e32 v50, v50
	s_waitcnt lgkmcnt(0)
	v_lshlrev_b32_e32 v51, 16, v51
	v_mul_f32_e32 v50, v130, v50
	v_mul_f32_e32 v50, v50, v51
	s_nop 1
	v_cvt_pk_bf16_f32 v50, v50, v1
	ds_write_b16 v114, v50
	v_add_f32_e32 v50, v126, v133
	v_mul_f32_e32 v50, 0x3fb8aa3b, v50
	v_exp_f32_e32 v50, v50
	ds_read_u16 v51, v104 offset:36512
	v_rcp_f32_e32 v50, v50
	s_waitcnt lgkmcnt(0)
	v_lshlrev_b32_e32 v51, 16, v51
	v_mul_f32_e32 v50, v130, v50
	v_mul_f32_e32 v50, v50, v51
	s_nop 1
	v_cvt_pk_bf16_f32 v50, v50, v1
	ds_write_b16 v115, v50
	v_add_f32_e32 v50, v127, v133
	v_mul_f32_e32 v50, 0x3fb8aa3b, v50
	v_exp_f32_e32 v50, v50
	ds_read_u16 v51, v104 offset:36784
	v_rcp_f32_e32 v50, v50
	s_waitcnt lgkmcnt(0)
	v_lshlrev_b32_e32 v51, 16, v51
	v_mul_f32_e32 v50, v130, v50
	v_mul_f32_e32 v50, v50, v51
	s_nop 1
	v_cvt_pk_bf16_f32 v50, v50, v1
	ds_write_b16 v116, v50
	v_add_f32_e32 v50, v128, v133
	v_mul_f32_e32 v50, 0x3fb8aa3b, v50
	v_exp_f32_e32 v50, v50
	ds_read_u16 v51, v104 offset:37056
	v_rcp_f32_e32 v50, v50
	s_waitcnt lgkmcnt(0)
	v_lshlrev_b32_e32 v51, 16, v51
	v_mul_f32_e32 v50, v130, v50
	v_mul_f32_e32 v50, v50, v51
	s_nop 1
	v_cvt_pk_bf16_f32 v50, v50, v1
	ds_write_b16 v117, v50
	v_add_f32_e32 v50, v129, v133
	v_mul_f32_e32 v50, 0x3fb8aa3b, v50
	v_exp_f32_e32 v50, v50
	ds_read_u16 v51, v104 offset:37328
	v_rcp_f32_e32 v50, v50
	s_waitcnt lgkmcnt(0)
	v_lshlrev_b32_e32 v51, 16, v51
	v_mul_f32_e32 v50, v130, v50
	v_mul_f32_e32 v50, v50, v51
	s_nop 1
	v_cvt_pk_bf16_f32 v50, v50, v1
	ds_write_b16 v118, v50
	v_add_f32_e32 v50, v131, v133
	v_mul_f32_e32 v50, 0x3fb8aa3b, v50
	v_exp_f32_e32 v50, v50
	ds_read_u16 v51, v104 offset:37600
	v_rcp_f32_e32 v50, v50
	s_waitcnt lgkmcnt(0)
	v_lshlrev_b32_e32 v51, 16, v51
	v_mul_f32_e32 v50, v130, v50
	v_mul_f32_e32 v50, v50, v51
	s_nop 1
	v_cvt_pk_bf16_f32 v50, v50, v1
	ds_write_b16 v119, v50
	v_add_f32_e32 v50, v133, v132
	v_mul_f32_e32 v50, 0x3fb8aa3b, v50
	v_exp_f32_e32 v50, v50
	ds_read_u16 v51, v104 offset:37872
	v_rcp_f32_e32 v50, v50
	s_waitcnt lgkmcnt(0)
	v_lshlrev_b32_e32 v51, 16, v51
	v_mul_f32_e32 v50, v130, v50
	v_mul_f32_e32 v50, v50, v51
	s_nop 1
	v_cvt_pk_bf16_f32 v50, v50, v1
	ds_write_b16 v120, v50
	s_cbranch_scc1 .LBB0_423
	v_lshl_add_u64 v[2:3], v[72:73], 0, s[20:21]
	v_lshl_add_u64 v[6:7], v[66:67], 0, s[20:21]
	flat_load_dwordx4 v[2:5], v[2:3]
	s_nop 0
	flat_load_dwordx4 v[6:9], v[6:7]
	v_lshl_add_u64 v[10:11], v[70:71], 0, s[20:21]
	v_lshl_add_u64 v[14:15], v[64:65], 0, s[20:21]
	v_lshl_add_u64 v[12:13], v[68:69], 0, s[20:21]
	v_lshl_add_u64 v[16:17], v[62:63], 0, s[20:21]
	flat_load_ushort v50, v[16:17]
	flat_load_ushort v51, v[12:13]
	s_nop 0
	flat_load_dwordx4 v[10:13], v[10:11]
	s_nop 0
	flat_load_dwordx4 v[14:17], v[14:15]
	s_waitcnt vmcnt(0) lgkmcnt(0)
	v_lshlrev_b32_e32 v60, 16, v50
	v_lshlrev_b32_e32 v61, 16, v51
	s_branch .LBB0_423
